# P2: next-unit first staging pair hoisted above epilogue stores, peeled first K-trip with C=0 (no acc zeroing) and relaxed vmcnt
# speedup vs baseline: 1.0130x; 1.0130x over previous
.LBB0_223:
	s_add_i32 s46, s20, 2
	s_add_u32 s22, s18, 0x80
	s_addc_u32 s21, s19, 0
	s_add_i32 s47, 0, 0x10000
	v_add_u32_e32 v164, s47, v158
	ds_read_b128 v[160:163], v164
	ds_read_b128 v[176:179], v164 offset:1024
	ds_read_b128 v[180:183], v164 offset:2048
	ds_read_b128 v[184:187], v164 offset:3072
	s_cmp_eq_u32 s38, s20
	s_cselect_b32 s20, s8, s22
	s_cselect_b32 s21, s9, s21
	s_cselect_b32 s23, s11, s45
	s_cselect_b32 s22, s10, s44
	v_lshl_add_u64 v[164:165], s[18:19], 0, v[156:157]
	s_add_i32 m0, s29, 0xc000
	ds_read_b128 v[188:191], v159
	ds_read_b128 v[192:195], v159 offset:1024
	ds_read_b128 v[196:199], v159 offset:2048
	ds_read_b128 v[200:203], v159 offset:3072
	ds_read_b128 v[204:207], v159 offset:4096
	ds_read_b128 v[218:221], v159 offset:5120
	ds_read_b128 v[224:227], v159 offset:6144
	ds_read_b128 v[228:231], v159 offset:7168
	global_load_lds_dwordx4 v[164:165], off
	v_lshl_add_u64 v[164:165], s[18:19], 0, v[154:155]
	s_add_i32 m0, s29, 0xe000
	s_nop 0
	global_load_lds_dwordx4 v[164:165], off
	s_waitcnt lgkmcnt(8)
	s_barrier
	s_waitcnt lgkmcnt(0)
	s_setprio 1
	s_waitcnt lgkmcnt(0)
	v_mfma_f32_16x16x32_bf16 v[124:127], v[160:163], v[188:191], v[124:127]
	v_mfma_f32_16x16x32_bf16 v[128:131], v[180:183], v[188:191], v[128:131]
	v_mfma_f32_16x16x32_bf16 v[112:115], v[160:163], v[196:199], v[112:115]
	v_mfma_f32_16x16x32_bf16 v[108:111], v[180:183], v[196:199], v[108:111]
	v_mfma_f32_16x16x32_bf16 v[96:99], v[160:163], v[204:207], v[96:99]
	v_mfma_f32_16x16x32_bf16 v[92:95], v[180:183], v[204:207], v[92:95]
	v_mfma_f32_16x16x32_bf16 v[76:79], v[160:163], v[224:227], v[76:79]
	v_mfma_f32_16x16x32_bf16 v[72:75], v[180:183], v[224:227], v[72:75]
	v_mfma_f32_16x16x32_bf16 v[124:127], v[176:179], v[192:195], v[124:127]
	v_mfma_f32_16x16x32_bf16 v[128:131], v[184:187], v[192:195], v[128:131]
	v_mfma_f32_16x16x32_bf16 v[112:115], v[176:179], v[200:203], v[112:115]
	v_mfma_f32_16x16x32_bf16 v[108:111], v[184:187], v[200:203], v[108:111]
	v_mfma_f32_16x16x32_bf16 v[96:99], v[176:179], v[218:221], v[96:99]
	v_mfma_f32_16x16x32_bf16 v[92:95], v[184:187], v[218:221], v[92:95]
	v_mfma_f32_16x16x32_bf16 v[76:79], v[176:179], v[228:231], v[76:79]
	v_mfma_f32_16x16x32_bf16 v[72:75], v[184:187], v[228:231], v[72:75]
	s_setprio 0
	s_barrier
	s_add_i32 s48, 0, 0x14000
	v_add_u32_e32 v164, s48, v158
	s_add_i32 s47, s47, s28
	ds_read_b128 v[232:235], v164
	ds_read_b128 v[236:239], v164 offset:1024
	ds_read_b128 v[240:243], v164 offset:2048
	ds_read_b128 v[244:247], v164 offset:3072
	v_lshl_add_u64 v[164:165], s[22:23], 0, v[166:167]
	s_mov_b32 m0, s47
	v_lshl_add_u64 v[248:249], s[22:23], 0, v[132:133]
	global_load_lds_dwordx4 v[164:165], off
	s_add_i32 m0, s47, 0x2000
	s_nop 0
	global_load_lds_dwordx4 v[248:249], off
	s_barrier
	s_waitcnt lgkmcnt(0)
	s_setprio 1
	s_waitcnt lgkmcnt(0)
	v_mfma_f32_16x16x32_bf16 v[120:123], v[232:235], v[188:191], v[120:123]
	v_mfma_f32_16x16x32_bf16 v[116:119], v[240:243], v[188:191], v[116:119]
	v_mfma_f32_16x16x32_bf16 v[104:107], v[232:235], v[196:199], v[104:107]
	v_mfma_f32_16x16x32_bf16 v[100:103], v[240:243], v[196:199], v[100:103]
	v_mfma_f32_16x16x32_bf16 v[88:91], v[232:235], v[204:207], v[88:91]
	v_mfma_f32_16x16x32_bf16 v[84:87], v[240:243], v[204:207], v[84:87]
	v_mfma_f32_16x16x32_bf16 v[68:71], v[232:235], v[224:227], v[68:71]
	v_mfma_f32_16x16x32_bf16 v[64:67], v[240:243], v[224:227], v[64:67]
	v_mfma_f32_16x16x32_bf16 v[120:123], v[236:239], v[192:195], v[120:123]
	v_mfma_f32_16x16x32_bf16 v[116:119], v[244:247], v[192:195], v[116:119]
	v_mfma_f32_16x16x32_bf16 v[104:107], v[236:239], v[200:203], v[104:107]
	v_mfma_f32_16x16x32_bf16 v[100:103], v[244:247], v[200:203], v[100:103]
	v_mfma_f32_16x16x32_bf16 v[88:91], v[236:239], v[218:221], v[88:91]
	v_mfma_f32_16x16x32_bf16 v[84:87], v[244:247], v[218:221], v[84:87]
	v_mfma_f32_16x16x32_bf16 v[68:71], v[236:239], v[228:231], v[68:71]
	v_mfma_f32_16x16x32_bf16 v[64:67], v[244:247], v[228:231], v[64:67]
	s_setprio 0
	s_mov_b32 m0, s29
	v_lshl_add_u64 v[250:251], s[20:21], 0, v[136:137]
	s_barrier
	ds_read_b128 v[188:191], v159 offset:16384
	ds_read_b128 v[192:195], v159 offset:17408
	ds_read_b128 v[196:199], v159 offset:18432
	ds_read_b128 v[200:203], v159 offset:19456
	ds_read_b128 v[204:207], v159 offset:20480
	ds_read_b128 v[218:221], v159 offset:21504
	ds_read_b128 v[224:227], v159 offset:22528
	ds_read_b128 v[228:231], v159 offset:23552
	global_load_lds_dwordx4 v[250:251], off
	v_lshl_add_u64 v[210:211], s[20:21], 0, v[134:135]
	s_mov_b32 m0, s30
	s_nop 0
	global_load_lds_dwordx4 v[210:211], off
	s_barrier
	s_waitcnt lgkmcnt(0)
	s_setprio 1
	s_waitcnt lgkmcnt(0)
	v_mfma_f32_16x16x32_bf16 v[60:63], v[160:163], v[188:191], v[60:63]
	v_mfma_f32_16x16x32_bf16 v[56:59], v[180:183], v[188:191], v[56:59]
	v_mfma_f32_16x16x32_bf16 v[44:47], v[160:163], v[196:199], v[44:47]
	v_mfma_f32_16x16x32_bf16 v[40:43], v[180:183], v[196:199], v[40:43]
	v_mfma_f32_16x16x32_bf16 v[28:31], v[160:163], v[204:207], v[28:31]
	v_mfma_f32_16x16x32_bf16 v[24:27], v[180:183], v[204:207], v[24:27]
	v_mfma_f32_16x16x32_bf16 v[12:15], v[160:163], v[224:227], v[12:15]
	v_mfma_f32_16x16x32_bf16 v[8:11], v[180:183], v[224:227], v[8:11]
	v_mfma_f32_16x16x32_bf16 v[60:63], v[176:179], v[192:195], v[60:63]
	v_mfma_f32_16x16x32_bf16 v[56:59], v[184:187], v[192:195], v[56:59]
	v_mfma_f32_16x16x32_bf16 v[44:47], v[176:179], v[200:203], v[44:47]
	v_mfma_f32_16x16x32_bf16 v[40:43], v[184:187], v[200:203], v[40:43]
	v_mfma_f32_16x16x32_bf16 v[28:31], v[176:179], v[218:221], v[28:31]
	v_mfma_f32_16x16x32_bf16 v[24:27], v[184:187], v[218:221], v[24:27]
	v_mfma_f32_16x16x32_bf16 v[12:15], v[176:179], v[228:231], v[12:15]
	v_mfma_f32_16x16x32_bf16 v[8:11], v[184:187], v[228:231], v[8:11]
	s_setprio 0
	s_barrier
	s_add_u32 s22, s22, s12
	s_addc_u32 s23, s23, s13
	s_add_i32 s47, s48, s28
	v_lshl_add_u64 v[170:171], s[22:23], 0, v[166:167]
	s_mov_b32 m0, s47
	v_lshl_add_u64 v[172:173], s[22:23], 0, v[132:133]
	global_load_lds_dwordx4 v[170:171], off
	s_add_i32 m0, s47, 0x2000
	s_nop 0
	global_load_lds_dwordx4 v[172:173], off
	s_waitcnt vmcnt(6)
	s_barrier
	s_setprio 1
	v_mfma_f32_16x16x32_bf16 v[52:55], v[232:235], v[188:191], v[52:55]
	v_mfma_f32_16x16x32_bf16 v[48:51], v[240:243], v[188:191], v[48:51]
	v_mfma_f32_16x16x32_bf16 v[36:39], v[232:235], v[196:199], v[36:39]
	v_mfma_f32_16x16x32_bf16 v[32:35], v[240:243], v[196:199], v[32:35]
	v_mfma_f32_16x16x32_bf16 v[20:23], v[232:235], v[204:207], v[20:23]
	v_mfma_f32_16x16x32_bf16 v[16:19], v[240:243], v[204:207], v[16:19]
	v_mfma_f32_16x16x32_bf16 v[4:7], v[232:235], v[224:227], v[4:7]
	v_mfma_f32_16x16x32_bf16 v[0:3], v[240:243], v[224:227], v[0:3]
	v_mfma_f32_16x16x32_bf16 v[52:55], v[236:239], v[192:195], v[52:55]
	v_mfma_f32_16x16x32_bf16 v[48:51], v[244:247], v[192:195], v[48:51]
	v_mfma_f32_16x16x32_bf16 v[36:39], v[236:239], v[200:203], v[36:39]
	v_mfma_f32_16x16x32_bf16 v[32:35], v[244:247], v[200:203], v[32:35]
	v_mfma_f32_16x16x32_bf16 v[20:23], v[236:239], v[218:221], v[20:23]
	v_mfma_f32_16x16x32_bf16 v[16:19], v[244:247], v[218:221], v[16:19]
	v_mfma_f32_16x16x32_bf16 v[4:7], v[236:239], v[228:231], v[4:7]
	v_mfma_f32_16x16x32_bf16 v[0:3], v[244:247], v[228:231], v[0:3]
	s_setprio 0
	s_add_i32 s22, 0, 0x18000
	v_add_u32_e32 v169, s22, v158
	s_barrier
	ds_read_b128 v[160:163], v169
	ds_read_b128 v[176:179], v169 offset:1024
	ds_read_b128 v[180:183], v169 offset:2048
	ds_read_b128 v[184:187], v169 offset:3072
	s_add_u32 s20, s20, s12
	s_addc_u32 s21, s21, s13
	s_mov_b32 m0, s31
	v_lshl_add_u64 v[232:233], s[20:21], 0, v[136:137]
	ds_read_b128 v[188:191], v159 offset:32768
	ds_read_b128 v[192:195], v159 offset:33792
	ds_read_b128 v[196:199], v159 offset:34816
	ds_read_b128 v[200:203], v159 offset:35840
	ds_read_b128 v[204:207], v159 offset:36864
	ds_read_b128 v[218:221], v159 offset:37888
	ds_read_b128 v[224:227], v159 offset:38912
	ds_read_b128 v[228:231], v159 offset:39936
	global_load_lds_dwordx4 v[232:233], off
	v_lshl_add_u64 v[232:233], s[20:21], 0, v[134:135]
	s_mov_b32 m0, s34
	s_nop 0
	global_load_lds_dwordx4 v[232:233], off
	s_waitcnt lgkmcnt(8)
	s_barrier
	s_waitcnt lgkmcnt(0)
	s_setprio 1
	s_waitcnt lgkmcnt(0)
	v_mfma_f32_16x16x32_bf16 v[124:127], v[160:163], v[188:191], v[124:127]
	v_mfma_f32_16x16x32_bf16 v[128:131], v[180:183], v[188:191], v[128:131]
	v_mfma_f32_16x16x32_bf16 v[112:115], v[160:163], v[196:199], v[112:115]
	v_mfma_f32_16x16x32_bf16 v[108:111], v[180:183], v[196:199], v[108:111]
	v_mfma_f32_16x16x32_bf16 v[96:99], v[160:163], v[204:207], v[96:99]
	v_mfma_f32_16x16x32_bf16 v[92:95], v[180:183], v[204:207], v[92:95]
	v_mfma_f32_16x16x32_bf16 v[76:79], v[160:163], v[224:227], v[76:79]
	v_mfma_f32_16x16x32_bf16 v[72:75], v[180:183], v[224:227], v[72:75]
	v_mfma_f32_16x16x32_bf16 v[124:127], v[176:179], v[192:195], v[124:127]
	v_mfma_f32_16x16x32_bf16 v[128:131], v[184:187], v[192:195], v[128:131]
	v_mfma_f32_16x16x32_bf16 v[112:115], v[176:179], v[200:203], v[112:115]
	v_mfma_f32_16x16x32_bf16 v[108:111], v[184:187], v[200:203], v[108:111]
	v_mfma_f32_16x16x32_bf16 v[96:99], v[176:179], v[218:221], v[96:99]
	v_mfma_f32_16x16x32_bf16 v[92:95], v[184:187], v[218:221], v[92:95]
	v_mfma_f32_16x16x32_bf16 v[76:79], v[176:179], v[228:231], v[76:79]
	v_mfma_f32_16x16x32_bf16 v[72:75], v[184:187], v[228:231], v[72:75]
	s_setprio 0
	s_barrier
	s_add_i32 s20, 0, 0x1c000
	s_add_i32 s21, s22, s28
	v_add_u32_e32 v169, s20, v158
	v_lshl_add_u64 v[164:165], v[164:165], 0, s[88:89]
	s_mov_b32 m0, s21
	ds_read_b128 v[232:235], v169
	ds_read_b128 v[236:239], v169 offset:1024
	ds_read_b128 v[240:243], v169 offset:2048
	ds_read_b128 v[244:247], v169 offset:3072
	global_load_lds_dwordx4 v[164:165], off
	v_lshl_add_u64 v[164:165], v[248:249], 0, s[88:89]
	s_add_i32 m0, s21, 0x2000
	s_nop 0
	global_load_lds_dwordx4 v[164:165], off
	s_barrier
	s_waitcnt lgkmcnt(0)
	s_setprio 1
	s_waitcnt lgkmcnt(0)
	v_mfma_f32_16x16x32_bf16 v[120:123], v[232:235], v[188:191], v[120:123]
	v_mfma_f32_16x16x32_bf16 v[116:119], v[240:243], v[188:191], v[116:119]
	v_mfma_f32_16x16x32_bf16 v[104:107], v[232:235], v[196:199], v[104:107]
	v_mfma_f32_16x16x32_bf16 v[100:103], v[240:243], v[196:199], v[100:103]
	v_mfma_f32_16x16x32_bf16 v[88:91], v[232:235], v[204:207], v[88:91]
	v_mfma_f32_16x16x32_bf16 v[84:87], v[240:243], v[204:207], v[84:87]
	v_mfma_f32_16x16x32_bf16 v[68:71], v[232:235], v[224:227], v[68:71]
	v_mfma_f32_16x16x32_bf16 v[64:67], v[240:243], v[224:227], v[64:67]
	v_mfma_f32_16x16x32_bf16 v[120:123], v[236:239], v[192:195], v[120:123]
	v_mfma_f32_16x16x32_bf16 v[116:119], v[244:247], v[192:195], v[116:119]
	v_mfma_f32_16x16x32_bf16 v[104:107], v[236:239], v[200:203], v[104:107]
	v_mfma_f32_16x16x32_bf16 v[100:103], v[244:247], v[200:203], v[100:103]
	v_mfma_f32_16x16x32_bf16 v[88:91], v[236:239], v[218:221], v[88:91]
	v_mfma_f32_16x16x32_bf16 v[84:87], v[244:247], v[218:221], v[84:87]
	v_mfma_f32_16x16x32_bf16 v[68:71], v[236:239], v[228:231], v[68:71]
	v_mfma_f32_16x16x32_bf16 v[64:67], v[244:247], v[228:231], v[64:67]
	s_setprio 0
	s_mov_b32 m0, s36
	v_lshl_add_u64 v[164:165], v[250:251], 0, s[88:89]
	s_barrier
	ds_read_b128 v[188:191], v159 offset:49152
	ds_read_b128 v[192:195], v159 offset:50176
	ds_read_b128 v[196:199], v159 offset:51200
	ds_read_b128 v[200:203], v159 offset:52224
	ds_read_b128 v[204:207], v159 offset:53248
	ds_read_b128 v[218:221], v159 offset:54272
	ds_read_b128 v[224:227], v159 offset:55296
	ds_read_b128 v[228:231], v159 offset:56320
	global_load_lds_dwordx4 v[164:165], off
	v_lshl_add_u64 v[164:165], v[210:211], 0, s[88:89]
	s_mov_b32 m0, s37
	s_nop 0
	global_load_lds_dwordx4 v[164:165], off
	s_barrier
	s_waitcnt lgkmcnt(0)
	s_setprio 1
	s_waitcnt lgkmcnt(0)
	v_mfma_f32_16x16x32_bf16 v[60:63], v[160:163], v[188:191], v[60:63]
	v_mfma_f32_16x16x32_bf16 v[56:59], v[180:183], v[188:191], v[56:59]
	v_mfma_f32_16x16x32_bf16 v[44:47], v[160:163], v[196:199], v[44:47]
	v_mfma_f32_16x16x32_bf16 v[40:43], v[180:183], v[196:199], v[40:43]
	v_mfma_f32_16x16x32_bf16 v[28:31], v[160:163], v[204:207], v[28:31]
	v_mfma_f32_16x16x32_bf16 v[24:27], v[180:183], v[204:207], v[24:27]
	v_mfma_f32_16x16x32_bf16 v[12:15], v[160:163], v[224:227], v[12:15]
	v_mfma_f32_16x16x32_bf16 v[8:11], v[180:183], v[224:227], v[8:11]
	v_mfma_f32_16x16x32_bf16 v[60:63], v[176:179], v[192:195], v[60:63]
	v_mfma_f32_16x16x32_bf16 v[56:59], v[184:187], v[192:195], v[56:59]
	v_mfma_f32_16x16x32_bf16 v[44:47], v[176:179], v[200:203], v[44:47]
	v_mfma_f32_16x16x32_bf16 v[40:43], v[184:187], v[200:203], v[40:43]
	v_mfma_f32_16x16x32_bf16 v[28:31], v[176:179], v[218:221], v[28:31]
	v_mfma_f32_16x16x32_bf16 v[24:27], v[184:187], v[218:221], v[24:27]
	v_mfma_f32_16x16x32_bf16 v[12:15], v[176:179], v[228:231], v[12:15]
	v_mfma_f32_16x16x32_bf16 v[8:11], v[184:187], v[228:231], v[8:11]
	s_setprio 0
	s_barrier
	s_add_i32 s20, s20, s28
	v_lshl_add_u64 v[160:161], v[170:171], 0, s[88:89]
	s_mov_b32 m0, s20
	s_nop 0
	global_load_lds_dwordx4 v[160:161], off
	v_lshl_add_u64 v[160:161], v[172:173], 0, s[88:89]
	s_add_i32 m0, s20, 0x2000
	s_nop 0
	global_load_lds_dwordx4 v[160:161], off
	s_waitcnt vmcnt(6)
	s_barrier
	s_setprio 1
	v_mfma_f32_16x16x32_bf16 v[52:55], v[232:235], v[188:191], v[52:55]
	v_mfma_f32_16x16x32_bf16 v[48:51], v[240:243], v[188:191], v[48:51]
	v_mfma_f32_16x16x32_bf16 v[36:39], v[232:235], v[196:199], v[36:39]
	v_mfma_f32_16x16x32_bf16 v[32:35], v[240:243], v[196:199], v[32:35]
	v_mfma_f32_16x16x32_bf16 v[20:23], v[232:235], v[204:207], v[20:23]
	v_mfma_f32_16x16x32_bf16 v[16:19], v[240:243], v[204:207], v[16:19]
	v_mfma_f32_16x16x32_bf16 v[4:7], v[232:235], v[224:227], v[4:7]
	v_mfma_f32_16x16x32_bf16 v[0:3], v[240:243], v[224:227], v[0:3]
	v_mfma_f32_16x16x32_bf16 v[52:55], v[236:239], v[192:195], v[52:55]
	v_mfma_f32_16x16x32_bf16 v[48:51], v[244:247], v[192:195], v[48:51]
	v_mfma_f32_16x16x32_bf16 v[36:39], v[236:239], v[200:203], v[36:39]
	v_mfma_f32_16x16x32_bf16 v[32:35], v[244:247], v[200:203], v[32:35]
	v_mfma_f32_16x16x32_bf16 v[20:23], v[236:239], v[218:221], v[20:23]
	v_mfma_f32_16x16x32_bf16 v[16:19], v[244:247], v[218:221], v[16:19]
	v_mfma_f32_16x16x32_bf16 v[4:7], v[236:239], v[228:231], v[4:7]
	v_mfma_f32_16x16x32_bf16 v[0:3], v[244:247], v[228:231], v[0:3]
	s_setprio 0
	s_add_u32 s44, s44, 0x100
	s_addc_u32 s45, s45, 0
	s_add_u32 s18, s18, 0x100
	s_addc_u32 s19, s19, 0
	s_cmp_ge_i32 s46, s35
	s_mov_b32 s20, s46
	s_barrier
	s_cbranch_scc0 .LBB0_223
	s_and_b64 vcc, exec, s[6:7]
	s_cbranch_vccz .Lp2_next
	s_mov_b32 s47, 0x28000
	v_mov_b64_e32 v[246:247], v[174:175]
	v_mov_b64_e32 v[174:175], v[216:217]
	v_mov_b32_e32 v217, v209
	v_mov_b32_e32 v209, 0x7f800000
	s_branch .LBB0_214
.Lp2_next:
	s_mul_i32 s18, s43, 49
	s_add_i32 s18, s18, s42
	s_ashr_i32 s19, s18, 31
	s_lshl_b64 s[18:19], s[18:19], 17
	v_lshl_add_u64 v[160:161], v[138:139], 0, s[18:19]
	v_cvt_pk_bf16_f32 v124, v124, v125
	v_cvt_pk_bf16_f32 v125, v126, v127
	v_cvt_pk_bf16_f32 v126, v128, v129
	v_cvt_pk_bf16_f32 v127, v130, v131
	v_cvt_pk_bf16_f32 v120, v120, v121
	v_cvt_pk_bf16_f32 v121, v122, v123
	v_cvt_pk_bf16_f32 v122, v116, v117
	v_cvt_pk_bf16_f32 v123, v118, v119
	v_lshl_add_u64 v[116:117], v[140:141], 0, s[18:19]
	v_cvt_pk_bf16_f32 v112, v112, v113
	v_cvt_pk_bf16_f32 v113, v114, v115
	v_cvt_pk_bf16_f32 v114, v108, v109
	v_cvt_pk_bf16_f32 v115, v110, v111
	v_cvt_pk_bf16_f32 v104, v104, v105
	v_cvt_pk_bf16_f32 v105, v106, v107
	v_cvt_pk_bf16_f32 v106, v100, v101
	v_cvt_pk_bf16_f32 v107, v102, v103
	v_lshl_add_u64 v[100:101], v[142:143], 0, s[18:19]
	v_cvt_pk_bf16_f32 v96, v96, v97
	v_cvt_pk_bf16_f32 v97, v98, v99
	v_cvt_pk_bf16_f32 v98, v92, v93
	v_cvt_pk_bf16_f32 v99, v94, v95
	v_cvt_pk_bf16_f32 v88, v88, v89
	v_cvt_pk_bf16_f32 v89, v90, v91
	v_cvt_pk_bf16_f32 v90, v84, v85
	v_cvt_pk_bf16_f32 v91, v86, v87
	v_lshl_add_u64 v[84:85], v[144:145], 0, s[18:19]
	v_cvt_pk_bf16_f32 v76, v76, v77
	v_cvt_pk_bf16_f32 v77, v78, v79
	v_cvt_pk_bf16_f32 v78, v72, v73
	v_cvt_pk_bf16_f32 v79, v74, v75
	v_cvt_pk_bf16_f32 v68, v68, v69
	v_cvt_pk_bf16_f32 v69, v70, v71
	v_cvt_pk_bf16_f32 v70, v64, v65
	v_cvt_pk_bf16_f32 v71, v66, v67
	v_lshl_add_u64 v[64:65], v[146:147], 0, s[18:19]
	v_cvt_pk_bf16_f32 v60, v60, v61
	v_cvt_pk_bf16_f32 v61, v62, v63
	v_cvt_pk_bf16_f32 v62, v56, v57
	v_cvt_pk_bf16_f32 v63, v58, v59
	v_cvt_pk_bf16_f32 v52, v52, v53
	v_cvt_pk_bf16_f32 v53, v54, v55
	v_cvt_pk_bf16_f32 v54, v48, v49
	v_cvt_pk_bf16_f32 v55, v50, v51
	v_lshl_add_u64 v[48:49], v[148:149], 0, s[18:19]
	v_cvt_pk_bf16_f32 v44, v44, v45
	v_cvt_pk_bf16_f32 v45, v46, v47
	v_cvt_pk_bf16_f32 v46, v40, v41
	v_cvt_pk_bf16_f32 v47, v42, v43
	v_cvt_pk_bf16_f32 v36, v36, v37
	v_cvt_pk_bf16_f32 v37, v38, v39
	v_cvt_pk_bf16_f32 v38, v32, v33
	v_cvt_pk_bf16_f32 v39, v34, v35
	v_lshl_add_u64 v[32:33], v[150:151], 0, s[18:19]
	v_cvt_pk_bf16_f32 v28, v28, v29
	v_cvt_pk_bf16_f32 v29, v30, v31
	v_cvt_pk_bf16_f32 v30, v24, v25
	v_cvt_pk_bf16_f32 v31, v26, v27
	v_cvt_pk_bf16_f32 v20, v20, v21
	v_cvt_pk_bf16_f32 v21, v22, v23
	v_cvt_pk_bf16_f32 v22, v16, v17
	v_cvt_pk_bf16_f32 v23, v18, v19
	v_lshl_add_u64 v[16:17], v[152:153], 0, s[18:19]
	v_cvt_pk_bf16_f32 v12, v12, v13
	v_cvt_pk_bf16_f32 v13, v14, v15
	v_cvt_pk_bf16_f32 v14, v8, v9
	v_cvt_pk_bf16_f32 v15, v10, v11
	v_cvt_pk_bf16_f32 v4, v4, v5
	v_cvt_pk_bf16_f32 v5, v6, v7
	v_cvt_pk_bf16_f32 v6, v0, v1
	v_cvt_pk_bf16_f32 v7, v2, v3
	s_mov_b32 s42, s40
	s_mov_b32 s43, s41
	s_mov_b64 s[20:21], s[8:9]
	s_mov_b64 s[18:19], s[10:11]
	s_add_u32 s22, s20, 0x80
	s_addc_u32 s23, s21, 0
	v_lshl_add_u64 v[164:165], s[22:23], 0, v[156:157]
	s_add_i32 m0, s29, 0xc000
	s_nop 0
	global_load_lds_dwordx4 v[164:165], off
	v_lshl_add_u64 v[164:165], s[22:23], 0, v[154:155]
	s_add_i32 m0, s29, 0xe000
	s_nop 0
	global_load_lds_dwordx4 v[164:165], off
	global_store_dwordx4 v[160:161], v[124:127], off nt
	global_store_dwordx4 v[160:161], v[120:123], off offset:256 nt
	global_store_dwordx4 v[116:117], v[112:115], off nt
	global_store_dwordx4 v[116:117], v[104:107], off offset:256 nt
	global_store_dwordx4 v[100:101], v[96:99], off nt
	global_store_dwordx4 v[100:101], v[88:91], off offset:256 nt
	global_store_dwordx4 v[84:85], v[76:79], off nt
	global_store_dwordx4 v[84:85], v[68:71], off offset:256 nt
	global_store_dwordx4 v[64:65], v[60:63], off nt
	global_store_dwordx4 v[64:65], v[52:55], off offset:256 nt
	global_store_dwordx4 v[48:49], v[44:47], off nt
	global_store_dwordx4 v[48:49], v[36:39], off offset:256 nt
	global_store_dwordx4 v[32:33], v[28:31], off nt
	global_store_dwordx4 v[32:33], v[20:23], off offset:256 nt
	global_store_dwordx4 v[16:17], v[12:15], off nt
	global_store_dwordx4 v[16:17], v[4:7], off offset:256 nt
	s_add_i32 s39, s39, 1
	s_mul_i32 s6, s3, s39
	s_mul_hi_u32 s7, s2, s39
	s_add_i32 s7, s7, s6
	s_mul_i32 s6, s2, s39
	s_add_u32 s10, s6, s64
	s_addc_u32 s11, s7, s65
	v_mov_b64_e32 v[0:1], 0xc40
	v_cmp_lt_i64_e64 s[8:9], s[10:11], v[0:1]
	v_mov_b64_e32 v[0:1], 0xc3f
	v_cmp_gt_i64_e64 s[6:7], s[10:11], v[0:1]
	s_and_b64 vcc, exec, s[6:7]
	s_cbranch_vccnz .Lp2_u217
	s_ashr_i32 s11, s10, 31
	s_lshr_b32 s11, s11, 29
	s_add_i32 s11, s10, s11
	s_ashr_i32 s22, s11, 3
	s_and_b32 s11, s11, -8
	s_sub_i32 s10, s10, s11
	s_cmp_lt_i32 s10, 0
	s_cselect_b32 s11, s69, 0x188
	s_mul_i32 s10, s10, s11
	s_add_i32 s10, s10, s22
	s_mul_hi_i32 s11, s10, 0x5397829d
	s_lshr_b32 s22, s11, 31
	s_ashr_i32 s11, s11, 6
	s_add_i32 s11, s11, s22
	s_lshl_b32 s22, s11, 2
	s_sub_i32 s23, 64, s22
	s_min_i32 s23, s23, 4
	s_abs_i32 s40, s23
	v_cvt_f32_u32_e32 v0, s40
	s_sub_i32 s44, 0, s40
	s_mulk_i32 s11, 0xc4
	s_sub_i32 s10, s10, s11
	v_rcp_iflag_f32_e32 v0, v0
	s_abs_i32 s11, s10
	s_xor_b32 s41, s10, s23
	s_ashr_i32 s41, s41, 31
	v_mul_f32_e32 v0, 0x4f7ffffe, v0
	v_cvt_u32_f32_e32 v0, v0
	s_nop 0
	v_readfirstlane_b32 s45, v0
	s_mul_i32 s44, s44, s45
	s_mul_hi_u32 s44, s45, s44
	s_add_i32 s45, s45, s44
	s_mul_hi_u32 s44, s11, s45
	s_mul_i32 s45, s44, s40
	s_sub_i32 s11, s11, s45
	s_add_i32 s46, s44, 1
	s_sub_i32 s45, s11, s40
	s_cmp_ge_u32 s11, s40
	s_cselect_b32 s44, s46, s44
	s_cselect_b32 s11, s45, s11
	s_add_i32 s45, s44, 1
	s_cmp_ge_u32 s11, s40
	s_cselect_b32 s11, s45, s44
	s_xor_b32 s11, s11, s41
	s_sub_i32 s40, s11, s41
	s_mul_i32 s11, s40, s23
	s_sub_i32 s10, s10, s11
	s_add_i32 s41, s22, s10

.Lp2_u221:
	s_add_u32 s44, s18, 0x100
	s_addc_u32 s45, s19, 0
	s_add_u32 s18, s20, 0x80
	s_addc_u32 s19, s21, 0
	s_mov_b32 s20, 0
	s_add_i32 s46, s20, 2
	s_add_u32 s22, s18, 0x80
	s_addc_u32 s21, s19, 0
	s_add_i32 s47, 0, 0x10000
	v_add_u32_e32 v164, s47, v158
	ds_read_b128 v[160:163], v164
	ds_read_b128 v[176:179], v164 offset:1024
	ds_read_b128 v[180:183], v164 offset:2048
	ds_read_b128 v[184:187], v164 offset:3072
	s_cmp_eq_u32 s38, s20
	s_cselect_b32 s20, s8, s22
	s_cselect_b32 s21, s9, s21
	s_cselect_b32 s23, s11, s45
	s_cselect_b32 s22, s10, s44
	ds_read_b128 v[188:191], v159
	ds_read_b128 v[192:195], v159 offset:1024
	ds_read_b128 v[196:199], v159 offset:2048
	ds_read_b128 v[200:203], v159 offset:3072
	ds_read_b128 v[204:207], v159 offset:4096
	ds_read_b128 v[218:221], v159 offset:5120
	ds_read_b128 v[224:227], v159 offset:6144
	ds_read_b128 v[228:231], v159 offset:7168
	v_lshl_add_u64 v[164:165], s[18:19], 0, v[154:155]
	s_waitcnt lgkmcnt(8)
	s_barrier
	s_waitcnt lgkmcnt(0)
	s_setprio 1
	s_waitcnt lgkmcnt(0)
	v_mfma_f32_16x16x32_bf16 v[124:127], v[160:163], v[188:191], 0
	v_mfma_f32_16x16x32_bf16 v[128:131], v[180:183], v[188:191], 0
	v_mfma_f32_16x16x32_bf16 v[112:115], v[160:163], v[196:199], 0
	v_mfma_f32_16x16x32_bf16 v[108:111], v[180:183], v[196:199], 0
	v_mfma_f32_16x16x32_bf16 v[96:99], v[160:163], v[204:207], 0
	v_mfma_f32_16x16x32_bf16 v[92:95], v[180:183], v[204:207], 0
	v_mfma_f32_16x16x32_bf16 v[76:79], v[160:163], v[224:227], 0
	v_mfma_f32_16x16x32_bf16 v[72:75], v[180:183], v[224:227], 0
	v_mfma_f32_16x16x32_bf16 v[124:127], v[176:179], v[192:195], v[124:127]
	v_mfma_f32_16x16x32_bf16 v[128:131], v[184:187], v[192:195], v[128:131]
	v_mfma_f32_16x16x32_bf16 v[112:115], v[176:179], v[200:203], v[112:115]
	v_mfma_f32_16x16x32_bf16 v[108:111], v[184:187], v[200:203], v[108:111]
	v_mfma_f32_16x16x32_bf16 v[96:99], v[176:179], v[218:221], v[96:99]
	v_mfma_f32_16x16x32_bf16 v[92:95], v[184:187], v[218:221], v[92:95]
	v_mfma_f32_16x16x32_bf16 v[76:79], v[176:179], v[228:231], v[76:79]
	v_mfma_f32_16x16x32_bf16 v[72:75], v[184:187], v[228:231], v[72:75]
	s_setprio 0
	s_barrier
	s_add_i32 s48, 0, 0x14000
	v_add_u32_e32 v164, s48, v158
	s_add_i32 s47, s47, s28
	ds_read_b128 v[232:235], v164
	ds_read_b128 v[236:239], v164 offset:1024
	ds_read_b128 v[240:243], v164 offset:2048
	ds_read_b128 v[244:247], v164 offset:3072
	v_lshl_add_u64 v[164:165], s[22:23], 0, v[166:167]
	s_mov_b32 m0, s47
	v_lshl_add_u64 v[248:249], s[22:23], 0, v[132:133]
	global_load_lds_dwordx4 v[164:165], off
	s_add_i32 m0, s47, 0x2000
	s_nop 0
	global_load_lds_dwordx4 v[248:249], off
	s_barrier
	s_waitcnt lgkmcnt(0)
	s_setprio 1
	s_waitcnt lgkmcnt(0)
	v_mfma_f32_16x16x32_bf16 v[120:123], v[232:235], v[188:191], 0
	v_mfma_f32_16x16x32_bf16 v[116:119], v[240:243], v[188:191], 0
	v_mfma_f32_16x16x32_bf16 v[104:107], v[232:235], v[196:199], 0
	v_mfma_f32_16x16x32_bf16 v[100:103], v[240:243], v[196:199], 0
	v_mfma_f32_16x16x32_bf16 v[88:91], v[232:235], v[204:207], 0
	v_mfma_f32_16x16x32_bf16 v[84:87], v[240:243], v[204:207], 0
	v_mfma_f32_16x16x32_bf16 v[68:71], v[232:235], v[224:227], 0
	v_mfma_f32_16x16x32_bf16 v[64:67], v[240:243], v[224:227], 0
	v_mfma_f32_16x16x32_bf16 v[120:123], v[236:239], v[192:195], v[120:123]
	v_mfma_f32_16x16x32_bf16 v[116:119], v[244:247], v[192:195], v[116:119]
	v_mfma_f32_16x16x32_bf16 v[104:107], v[236:239], v[200:203], v[104:107]
	v_mfma_f32_16x16x32_bf16 v[100:103], v[244:247], v[200:203], v[100:103]
	v_mfma_f32_16x16x32_bf16 v[88:91], v[236:239], v[218:221], v[88:91]
	v_mfma_f32_16x16x32_bf16 v[84:87], v[244:247], v[218:221], v[84:87]
	v_mfma_f32_16x16x32_bf16 v[68:71], v[236:239], v[228:231], v[68:71]
	v_mfma_f32_16x16x32_bf16 v[64:67], v[244:247], v[228:231], v[64:67]
	s_setprio 0
	s_mov_b32 m0, s29
	v_lshl_add_u64 v[250:251], s[20:21], 0, v[136:137]
	s_barrier
	ds_read_b128 v[188:191], v159 offset:16384
	ds_read_b128 v[192:195], v159 offset:17408
	ds_read_b128 v[196:199], v159 offset:18432
	ds_read_b128 v[200:203], v159 offset:19456
	ds_read_b128 v[204:207], v159 offset:20480
	ds_read_b128 v[218:221], v159 offset:21504
	ds_read_b128 v[224:227], v159 offset:22528
	ds_read_b128 v[228:231], v159 offset:23552
	global_load_lds_dwordx4 v[250:251], off
	v_lshl_add_u64 v[210:211], s[20:21], 0, v[134:135]
	s_mov_b32 m0, s30
	s_nop 0
	global_load_lds_dwordx4 v[210:211], off
	s_barrier
	s_waitcnt lgkmcnt(0)
	s_setprio 1
	s_waitcnt lgkmcnt(0)
	v_mfma_f32_16x16x32_bf16 v[60:63], v[160:163], v[188:191], 0
	v_mfma_f32_16x16x32_bf16 v[56:59], v[180:183], v[188:191], 0
	v_mfma_f32_16x16x32_bf16 v[44:47], v[160:163], v[196:199], 0
	v_mfma_f32_16x16x32_bf16 v[40:43], v[180:183], v[196:199], 0
	v_mfma_f32_16x16x32_bf16 v[28:31], v[160:163], v[204:207], 0
	v_mfma_f32_16x16x32_bf16 v[24:27], v[180:183], v[204:207], 0
	v_mfma_f32_16x16x32_bf16 v[12:15], v[160:163], v[224:227], 0
	v_mfma_f32_16x16x32_bf16 v[8:11], v[180:183], v[224:227], 0
	v_mfma_f32_16x16x32_bf16 v[60:63], v[176:179], v[192:195], v[60:63]
	v_mfma_f32_16x16x32_bf16 v[56:59], v[184:187], v[192:195], v[56:59]
	v_mfma_f32_16x16x32_bf16 v[44:47], v[176:179], v[200:203], v[44:47]
	v_mfma_f32_16x16x32_bf16 v[40:43], v[184:187], v[200:203], v[40:43]
	v_mfma_f32_16x16x32_bf16 v[28:31], v[176:179], v[218:221], v[28:31]
	v_mfma_f32_16x16x32_bf16 v[24:27], v[184:187], v[218:221], v[24:27]
	v_mfma_f32_16x16x32_bf16 v[12:15], v[176:179], v[228:231], v[12:15]
	v_mfma_f32_16x16x32_bf16 v[8:11], v[184:187], v[228:231], v[8:11]
	s_setprio 0
	s_barrier
	s_add_u32 s22, s22, s12
	s_addc_u32 s23, s23, s13
	s_add_i32 s47, s48, s28
	v_lshl_add_u64 v[170:171], s[22:23], 0, v[166:167]
	s_mov_b32 m0, s47
	v_lshl_add_u64 v[172:173], s[22:23], 0, v[132:133]
	global_load_lds_dwordx4 v[170:171], off
	s_add_i32 m0, s47, 0x2000
	s_nop 0
	global_load_lds_dwordx4 v[172:173], off
	s_waitcnt vmcnt(22)
	s_barrier
	s_setprio 1
	v_mfma_f32_16x16x32_bf16 v[52:55], v[232:235], v[188:191], 0
	v_mfma_f32_16x16x32_bf16 v[48:51], v[240:243], v[188:191], 0
	v_mfma_f32_16x16x32_bf16 v[36:39], v[232:235], v[196:199], 0
	v_mfma_f32_16x16x32_bf16 v[32:35], v[240:243], v[196:199], 0
	v_mfma_f32_16x16x32_bf16 v[20:23], v[232:235], v[204:207], 0
	v_mfma_f32_16x16x32_bf16 v[16:19], v[240:243], v[204:207], 0
	v_mfma_f32_16x16x32_bf16 v[4:7], v[232:235], v[224:227], 0
	v_mfma_f32_16x16x32_bf16 v[0:3], v[240:243], v[224:227], 0
	v_mfma_f32_16x16x32_bf16 v[52:55], v[236:239], v[192:195], v[52:55]
	v_mfma_f32_16x16x32_bf16 v[48:51], v[244:247], v[192:195], v[48:51]
	v_mfma_f32_16x16x32_bf16 v[36:39], v[236:239], v[200:203], v[36:39]
	v_mfma_f32_16x16x32_bf16 v[32:35], v[244:247], v[200:203], v[32:35]
	v_mfma_f32_16x16x32_bf16 v[20:23], v[236:239], v[218:221], v[20:23]
	v_mfma_f32_16x16x32_bf16 v[16:19], v[244:247], v[218:221], v[16:19]
	v_mfma_f32_16x16x32_bf16 v[4:7], v[236:239], v[228:231], v[4:7]
	v_mfma_f32_16x16x32_bf16 v[0:3], v[244:247], v[228:231], v[0:3]
	s_setprio 0
	s_add_i32 s22, 0, 0x18000
	v_add_u32_e32 v169, s22, v158
	s_barrier
	ds_read_b128 v[160:163], v169
	ds_read_b128 v[176:179], v169 offset:1024
	ds_read_b128 v[180:183], v169 offset:2048
	ds_read_b128 v[184:187], v169 offset:3072
	s_add_u32 s20, s20, s12
	s_addc_u32 s21, s21, s13
	s_mov_b32 m0, s31
	v_lshl_add_u64 v[232:233], s[20:21], 0, v[136:137]
	ds_read_b128 v[188:191], v159 offset:32768
	ds_read_b128 v[192:195], v159 offset:33792
	ds_read_b128 v[196:199], v159 offset:34816
	ds_read_b128 v[200:203], v159 offset:35840
	ds_read_b128 v[204:207], v159 offset:36864
	ds_read_b128 v[218:221], v159 offset:37888
	ds_read_b128 v[224:227], v159 offset:38912
	ds_read_b128 v[228:231], v159 offset:39936
	global_load_lds_dwordx4 v[232:233], off
	v_lshl_add_u64 v[232:233], s[20:21], 0, v[134:135]
	s_mov_b32 m0, s34
	s_nop 0
	global_load_lds_dwordx4 v[232:233], off
	s_waitcnt lgkmcnt(8)
	s_barrier
	s_waitcnt lgkmcnt(0)
	s_setprio 1
	s_waitcnt lgkmcnt(0)
	v_mfma_f32_16x16x32_bf16 v[124:127], v[160:163], v[188:191], v[124:127]
	v_mfma_f32_16x16x32_bf16 v[128:131], v[180:183], v[188:191], v[128:131]
	v_mfma_f32_16x16x32_bf16 v[112:115], v[160:163], v[196:199], v[112:115]
	v_mfma_f32_16x16x32_bf16 v[108:111], v[180:183], v[196:199], v[108:111]
	v_mfma_f32_16x16x32_bf16 v[96:99], v[160:163], v[204:207], v[96:99]
	v_mfma_f32_16x16x32_bf16 v[92:95], v[180:183], v[204:207], v[92:95]
	v_mfma_f32_16x16x32_bf16 v[76:79], v[160:163], v[224:227], v[76:79]
	v_mfma_f32_16x16x32_bf16 v[72:75], v[180:183], v[224:227], v[72:75]
	v_mfma_f32_16x16x32_bf16 v[124:127], v[176:179], v[192:195], v[124:127]
	v_mfma_f32_16x16x32_bf16 v[128:131], v[184:187], v[192:195], v[128:131]
	v_mfma_f32_16x16x32_bf16 v[112:115], v[176:179], v[200:203], v[112:115]
	v_mfma_f32_16x16x32_bf16 v[108:111], v[184:187], v[200:203], v[108:111]
	v_mfma_f32_16x16x32_bf16 v[96:99], v[176:179], v[218:221], v[96:99]
	v_mfma_f32_16x16x32_bf16 v[92:95], v[184:187], v[218:221], v[92:95]
	v_mfma_f32_16x16x32_bf16 v[76:79], v[176:179], v[228:231], v[76:79]
	v_mfma_f32_16x16x32_bf16 v[72:75], v[184:187], v[228:231], v[72:75]
	s_setprio 0
	s_barrier
	s_add_i32 s20, 0, 0x1c000
	s_add_i32 s21, s22, s28
	v_add_u32_e32 v169, s20, v158
	v_lshl_add_u64 v[164:165], v[164:165], 0, s[88:89]
	s_mov_b32 m0, s21
	ds_read_b128 v[232:235], v169
	ds_read_b128 v[236:239], v169 offset:1024
	ds_read_b128 v[240:243], v169 offset:2048
	ds_read_b128 v[244:247], v169 offset:3072
	global_load_lds_dwordx4 v[164:165], off
	v_lshl_add_u64 v[164:165], v[248:249], 0, s[88:89]
	s_add_i32 m0, s21, 0x2000
	s_nop 0
	global_load_lds_dwordx4 v[164:165], off
	s_barrier
	s_waitcnt lgkmcnt(0)
	s_setprio 1
	s_waitcnt lgkmcnt(0)
	v_mfma_f32_16x16x32_bf16 v[120:123], v[232:235], v[188:191], v[120:123]
	v_mfma_f32_16x16x32_bf16 v[116:119], v[240:243], v[188:191], v[116:119]
	v_mfma_f32_16x16x32_bf16 v[104:107], v[232:235], v[196:199], v[104:107]
	v_mfma_f32_16x16x32_bf16 v[100:103], v[240:243], v[196:199], v[100:103]
	v_mfma_f32_16x16x32_bf16 v[88:91], v[232:235], v[204:207], v[88:91]
	v_mfma_f32_16x16x32_bf16 v[84:87], v[240:243], v[204:207], v[84:87]
	v_mfma_f32_16x16x32_bf16 v[68:71], v[232:235], v[224:227], v[68:71]
	v_mfma_f32_16x16x32_bf16 v[64:67], v[240:243], v[224:227], v[64:67]
	v_mfma_f32_16x16x32_bf16 v[120:123], v[236:239], v[192:195], v[120:123]
	v_mfma_f32_16x16x32_bf16 v[116:119], v[244:247], v[192:195], v[116:119]
	v_mfma_f32_16x16x32_bf16 v[104:107], v[236:239], v[200:203], v[104:107]
	v_mfma_f32_16x16x32_bf16 v[100:103], v[244:247], v[200:203], v[100:103]
	v_mfma_f32_16x16x32_bf16 v[88:91], v[236:239], v[218:221], v[88:91]
	v_mfma_f32_16x16x32_bf16 v[84:87], v[244:247], v[218:221], v[84:87]
	v_mfma_f32_16x16x32_bf16 v[68:71], v[236:239], v[228:231], v[68:71]
	v_mfma_f32_16x16x32_bf16 v[64:67], v[244:247], v[228:231], v[64:67]
	s_setprio 0
	s_mov_b32 m0, s36
	v_lshl_add_u64 v[164:165], v[250:251], 0, s[88:89]
	s_barrier
	ds_read_b128 v[188:191], v159 offset:49152
	ds_read_b128 v[192:195], v159 offset:50176
	ds_read_b128 v[196:199], v159 offset:51200
	ds_read_b128 v[200:203], v159 offset:52224
	ds_read_b128 v[204:207], v159 offset:53248
	ds_read_b128 v[218:221], v159 offset:54272
	ds_read_b128 v[224:227], v159 offset:55296
	ds_read_b128 v[228:231], v159 offset:56320
	global_load_lds_dwordx4 v[164:165], off
	v_lshl_add_u64 v[164:165], v[210:211], 0, s[88:89]
	s_mov_b32 m0, s37
	s_nop 0
	global_load_lds_dwordx4 v[164:165], off
	s_barrier
	s_waitcnt lgkmcnt(0)
	s_setprio 1
	s_waitcnt lgkmcnt(0)
	v_mfma_f32_16x16x32_bf16 v[60:63], v[160:163], v[188:191], v[60:63]
	v_mfma_f32_16x16x32_bf16 v[56:59], v[180:183], v[188:191], v[56:59]
	v_mfma_f32_16x16x32_bf16 v[44:47], v[160:163], v[196:199], v[44:47]
	v_mfma_f32_16x16x32_bf16 v[40:43], v[180:183], v[196:199], v[40:43]
	v_mfma_f32_16x16x32_bf16 v[28:31], v[160:163], v[204:207], v[28:31]
	v_mfma_f32_16x16x32_bf16 v[24:27], v[180:183], v[204:207], v[24:27]
	v_mfma_f32_16x16x32_bf16 v[12:15], v[160:163], v[224:227], v[12:15]
	v_mfma_f32_16x16x32_bf16 v[8:11], v[180:183], v[224:227], v[8:11]
	v_mfma_f32_16x16x32_bf16 v[60:63], v[176:179], v[192:195], v[60:63]
	v_mfma_f32_16x16x32_bf16 v[56:59], v[184:187], v[192:195], v[56:59]
	v_mfma_f32_16x16x32_bf16 v[44:47], v[176:179], v[200:203], v[44:47]
	v_mfma_f32_16x16x32_bf16 v[40:43], v[184:187], v[200:203], v[40:43]
	v_mfma_f32_16x16x32_bf16 v[28:31], v[176:179], v[218:221], v[28:31]
	v_mfma_f32_16x16x32_bf16 v[24:27], v[184:187], v[218:221], v[24:27]
	v_mfma_f32_16x16x32_bf16 v[12:15], v[176:179], v[228:231], v[12:15]
	v_mfma_f32_16x16x32_bf16 v[8:11], v[184:187], v[228:231], v[8:11]
	s_setprio 0
	s_barrier
	s_add_i32 s20, s20, s28
	v_lshl_add_u64 v[160:161], v[170:171], 0, s[88:89]
	s_mov_b32 m0, s20
	s_nop 0
	global_load_lds_dwordx4 v[160:161], off
	v_lshl_add_u64 v[160:161], v[172:173], 0, s[88:89]
	s_add_i32 m0, s20, 0x2000
	s_nop 0
	global_load_lds_dwordx4 v[160:161], off
	s_waitcnt vmcnt(6)
	s_barrier
	s_setprio 1
	v_mfma_f32_16x16x32_bf16 v[52:55], v[232:235], v[188:191], v[52:55]
	v_mfma_f32_16x16x32_bf16 v[48:51], v[240:243], v[188:191], v[48:51]
	v_mfma_f32_16x16x32_bf16 v[36:39], v[232:235], v[196:199], v[36:39]
	v_mfma_f32_16x16x32_bf16 v[32:35], v[240:243], v[196:199], v[32:35]
	v_mfma_f32_16x16x32_bf16 v[20:23], v[232:235], v[204:207], v[20:23]
	v_mfma_f32_16x16x32_bf16 v[16:19], v[240:243], v[204:207], v[16:19]
	v_mfma_f32_16x16x32_bf16 v[4:7], v[232:235], v[224:227], v[4:7]
	v_mfma_f32_16x16x32_bf16 v[0:3], v[240:243], v[224:227], v[0:3]
	v_mfma_f32_16x16x32_bf16 v[52:55], v[236:239], v[192:195], v[52:55]
	v_mfma_f32_16x16x32_bf16 v[48:51], v[244:247], v[192:195], v[48:51]
	v_mfma_f32_16x16x32_bf16 v[36:39], v[236:239], v[200:203], v[36:39]
	v_mfma_f32_16x16x32_bf16 v[32:35], v[244:247], v[200:203], v[32:35]
	v_mfma_f32_16x16x32_bf16 v[20:23], v[236:239], v[218:221], v[20:23]
	v_mfma_f32_16x16x32_bf16 v[16:19], v[244:247], v[218:221], v[16:19]
	v_mfma_f32_16x16x32_bf16 v[4:7], v[236:239], v[228:231], v[4:7]
	v_mfma_f32_16x16x32_bf16 v[0:3], v[244:247], v[228:231], v[0:3]
	s_setprio 0
	s_add_u32 s44, s44, 0x100
	s_addc_u32 s45, s45, 0
	s_add_u32 s18, s18, 0x100
	s_addc_u32 s19, s19, 0
	s_mov_b32 s20, s46
	s_barrier
	s_branch .LBB0_223
